# softmax: running-max-moved branch and O rescale moved behind the exps and row sum (math unchanged); otherwise as previous best
# speedup vs baseline: 1.0015x; 1.0015x over previous
; template <int NS, int SI>
; __device__ __forceinline__ void attn_stream(const unsigned char* kbase, const unsigned char* vbase, const unsigned char* q_rd, bool mask_tail, int last_valid, int hh, float sc,
;                                             f32x16 (&O)[4], float& mrun, float& lrun) {
;     ...
;     const float mn = fmaxf(mrun, mx * sc);
;     const float alpha = __builtin_amdgcn_exp2f(mrun - mn);
;     mrun = mn;
;     f32x2 ls2 = {0.f, 0.f};
;     const f32x2 sc2 = {sc, sc}, mn2 = {mn, mn};
; #pragma unroll
;     for (int r = 0; r < 16; r += 2) {
;         const f32x2 t0 = (f32x2){S0[r], S0[r + 1]} * sc2 - mn2, t1 = (f32x2){S1[r], S1[r + 1]} * sc2 - mn2;
;         const f32x2 p0 = {__builtin_amdgcn_exp2f(t0.x), __builtin_amdgcn_exp2f(t0.y)}, p1 = {__builtin_amdgcn_exp2f(t1.x), __builtin_amdgcn_exp2f(t1.y)};
;         S0[r] = p0.x; S0[r + 1] = p0.y; S1[r] = p1.x; S1[r + 1] = p1.y; ls2 += p0 + p1;
;     }
;     lrun = lrun * alpha + (ls2.x + ls2.y);
;     if (__any(alpha != 1.0f)) {
; #pragma unroll
;         for (int d = 0; d < 4; ++d) O[d] = O[d] * alpha;
.LBB0_1167:
	v_pk_fma_f32 v[128:129], v[128:129], s[58:59], v[200:201] op_sel_hi:[1,0,0] neg_lo:[0,0,1] neg_hi:[0,0,1]
	v_pk_fma_f32 v[144:145], v[144:145], s[58:59], v[200:201] op_sel_hi:[1,0,0] neg_lo:[0,0,1] neg_hi:[0,0,1]
	v_exp_f32_e32 v232, v128
	v_exp_f32_e32 v233, v129
	v_exp_f32_e32 v144, v144
	v_exp_f32_e32 v145, v145
	v_pk_fma_f32 v[128:129], v[130:131], s[58:59], v[200:201] op_sel_hi:[1,0,0] neg_lo:[0,0,1] neg_hi:[0,0,1]
	v_pk_fma_f32 v[130:131], v[146:147], s[58:59], v[200:201] op_sel_hi:[1,0,0] neg_lo:[0,0,1] neg_hi:[0,0,1]
	v_exp_f32_e32 v146, v128
	v_exp_f32_e32 v147, v129
	v_exp_f32_e32 v234, v130
	v_exp_f32_e32 v235, v131
	v_pk_fma_f32 v[132:133], v[132:133], s[58:59], v[200:201] op_sel_hi:[1,0,0] neg_lo:[0,0,1] neg_hi:[0,0,1]
	v_pk_fma_f32 v[148:149], v[148:149], s[58:59], v[200:201] op_sel_hi:[1,0,0] neg_lo:[0,0,1] neg_hi:[0,0,1]
	v_exp_f32_e32 v236, v132
	v_exp_f32_e32 v237, v133
	v_exp_f32_e32 v148, v148
	v_exp_f32_e32 v149, v149
	v_pk_fma_f32 v[132:133], v[134:135], s[58:59], v[200:201] op_sel_hi:[1,0,0] neg_lo:[0,0,1] neg_hi:[0,0,1]
	v_pk_fma_f32 v[134:135], v[150:151], s[58:59], v[200:201] op_sel_hi:[1,0,0] neg_lo:[0,0,1] neg_hi:[0,0,1]
	v_exp_f32_e32 v150, v132
	v_exp_f32_e32 v151, v133
	v_exp_f32_e32 v238, v134
	v_exp_f32_e32 v239, v135
	v_pk_fma_f32 v[132:133], v[136:137], s[58:59], v[200:201] op_sel_hi:[1,0,0] neg_lo:[0,0,1] neg_hi:[0,0,1]
	v_pk_fma_f32 v[134:135], v[152:153], s[58:59], v[200:201] op_sel_hi:[1,0,0] neg_lo:[0,0,1] neg_hi:[0,0,1]
	v_pk_add_f32 v[128:129], v[144:145], v[232:233]
	v_exp_f32_e32 v152, v132
	v_exp_f32_e32 v153, v133
	v_exp_f32_e32 v240, v134
	v_exp_f32_e32 v241, v135
	v_pk_fma_f32 v[132:133], v[138:139], s[58:59], v[200:201] op_sel_hi:[1,0,0] neg_lo:[0,0,1] neg_hi:[0,0,1]
	v_pk_fma_f32 v[134:135], v[154:155], s[58:59], v[200:201] op_sel_hi:[1,0,0] neg_lo:[0,0,1] neg_hi:[0,0,1]
	v_pk_add_f32 v[130:131], v[234:235], v[146:147]
	v_exp_f32_e32 v154, v132
	v_exp_f32_e32 v155, v133
	v_exp_f32_e32 v242, v134
	v_exp_f32_e32 v243, v135
	v_pk_fma_f32 v[132:133], v[140:141], s[58:59], v[200:201] op_sel_hi:[1,0,0] neg_lo:[0,0,1] neg_hi:[0,0,1]
	v_pk_fma_f32 v[134:135], v[156:157], s[58:59], v[200:201] op_sel_hi:[1,0,0] neg_lo:[0,0,1] neg_hi:[0,0,1]
	v_pk_add_f32 v[128:129], v[130:131], v[128:129]
	v_pk_add_f32 v[130:131], v[148:149], v[236:237]
	v_exp_f32_e32 v140, v132
	v_exp_f32_e32 v141, v133
	v_exp_f32_e32 v156, v134
	v_exp_f32_e32 v157, v135
	v_pk_fma_f32 v[132:133], v[142:143], s[58:59], v[200:201] op_sel_hi:[1,0,0] neg_lo:[0,0,1] neg_hi:[0,0,1]
	v_pk_fma_f32 v[134:135], v[158:159], s[58:59], v[200:201] op_sel_hi:[1,0,0] neg_lo:[0,0,1] neg_hi:[0,0,1]
	v_pk_add_f32 v[128:129], v[130:131], v[128:129]
	v_pk_add_f32 v[130:131], v[238:239], v[150:151]
	v_exp_f32_e32 v142, v132
	v_exp_f32_e32 v143, v133
	v_exp_f32_e32 v158, v134
	v_exp_f32_e32 v159, v135
	v_pk_add_f32 v[128:129], v[130:131], v[128:129]
	v_pk_add_f32 v[130:131], v[240:241], v[152:153]
	v_pk_add_f32 v[132:133], v[242:243], v[154:155]
	v_pk_add_f32 v[134:135], v[156:157], v[140:141]
	v_pk_add_f32 v[136:137], v[158:159], v[142:143]
	v_pk_add_f32 v[128:129], v[130:131], v[128:129]
	v_pk_add_f32 v[132:133], v[134:135], v[132:133]
	v_pk_add_f32 v[128:129], v[136:137], v[128:129]
	v_pk_add_f32 v[128:129], v[132:133], v[128:129]
	v_add_f32_e32 v231, v128, v129
	s_cbranch_vccz .Lsm0_norescale
	v_sub_f32_e32 v202, v228, v200
	v_exp_f32_e32 v202, v202
	s_nop 0
	v_pk_mul_f32 v[78:79], v[78:79], v[202:203] op_sel_hi:[1,0]
	v_pk_mul_f32 v[76:77], v[76:77], v[202:203] op_sel_hi:[1,0]
	v_pk_mul_f32 v[74:75], v[74:75], v[202:203] op_sel_hi:[1,0]
	v_pk_mul_f32 v[72:73], v[72:73], v[202:203] op_sel_hi:[1,0]
	v_pk_mul_f32 v[70:71], v[70:71], v[202:203] op_sel_hi:[1,0]
	v_pk_mul_f32 v[68:69], v[68:69], v[202:203] op_sel_hi:[1,0]
	v_pk_mul_f32 v[66:67], v[66:67], v[202:203] op_sel_hi:[1,0]
	v_pk_mul_f32 v[64:65], v[64:65], v[202:203] op_sel_hi:[1,0]
	v_pk_mul_f32 v[62:63], v[62:63], v[202:203] op_sel_hi:[1,0]
	v_pk_mul_f32 v[60:61], v[60:61], v[202:203] op_sel_hi:[1,0]
	v_pk_mul_f32 v[58:59], v[58:59], v[202:203] op_sel_hi:[1,0]
	v_pk_mul_f32 v[56:57], v[56:57], v[202:203] op_sel_hi:[1,0]
	v_pk_mul_f32 v[54:55], v[54:55], v[202:203] op_sel_hi:[1,0]
	v_pk_mul_f32 v[52:53], v[52:53], v[202:203] op_sel_hi:[1,0]
	v_pk_mul_f32 v[50:51], v[50:51], v[202:203] op_sel_hi:[1,0]
	v_pk_mul_f32 v[48:49], v[48:49], v[202:203] op_sel_hi:[1,0]
	v_pk_mul_f32 v[46:47], v[46:47], v[202:203] op_sel_hi:[1,0]
	v_pk_mul_f32 v[44:45], v[44:45], v[202:203] op_sel_hi:[1,0]
	v_pk_mul_f32 v[42:43], v[42:43], v[202:203] op_sel_hi:[1,0]
	v_pk_mul_f32 v[40:41], v[40:41], v[202:203] op_sel_hi:[1,0]
	v_pk_mul_f32 v[38:39], v[38:39], v[202:203] op_sel_hi:[1,0]
	v_pk_mul_f32 v[36:37], v[36:37], v[202:203] op_sel_hi:[1,0]
	v_pk_mul_f32 v[34:35], v[34:35], v[202:203] op_sel_hi:[1,0]
	v_pk_mul_f32 v[32:33], v[32:33], v[202:203] op_sel_hi:[1,0]
	v_pk_mul_f32 v[14:15], v[14:15], v[202:203] op_sel_hi:[1,0]
	v_pk_mul_f32 v[12:13], v[12:13], v[202:203] op_sel_hi:[1,0]
	v_pk_mul_f32 v[10:11], v[10:11], v[202:203] op_sel_hi:[1,0]
	v_pk_mul_f32 v[8:9], v[8:9], v[202:203] op_sel_hi:[1,0]
	v_pk_mul_f32 v[6:7], v[6:7], v[202:203] op_sel_hi:[1,0]
	v_pk_mul_f32 v[4:5], v[4:5], v[202:203] op_sel_hi:[1,0]
	v_pk_mul_f32 v[2:3], v[2:3], v[202:203] op_sel_hi:[1,0]
	v_pk_mul_f32 v[0:1], v[0:1], v[202:203] op_sel_hi:[1,0]
; template <int NS, int SI>
; __device__ __forceinline__ void attn_stream(const unsigned char* kbase, const unsigned char* vbase, const unsigned char* q_rd, bool mask_tail, int last_valid, int hh, float sc,
;                                             f32x16 (&O)[4], float& mrun, float& lrun) {
;     ...
;     lrun = lrun * alpha + (ls2.x + ls2.y);
;     if (__any(alpha != 1.0f)) {
; #pragma unroll
;         for (int d = 0; d < 4; ++d) O[d] = O[d] * alpha;
;     }
;     ...
;     __builtin_amdgcn_sched_barrier(0);
;     PV_GROUP(S0, 0, 0) PV_GROUP(S0, 0, 1) PV_GROUP(S1, 1, 0) PV_GROUP(S1, 1, 1)
.Lsm0_norescale:
	v_fmac_f32_e32 v231, v226, v202
	ds_read_b64_tr_b16 v[128:129], v225 offset:17408
	ds_read_b64_tr_b16 v[130:131], v225 offset:19968
	ds_read_b64_tr_b16 v[138:139], v225 offset:20032
	ds_read_b64_tr_b16 v[136:137], v225 offset:17472
	v_cvt_pk_bf16_f32 v132, v232, v233
	v_cvt_pk_bf16_f32 v133, v146, v147
	v_cvt_pk_bf16_f32 v134, v236, v237
	v_cvt_pk_bf16_f32 v135, v150, v151
	s_waitcnt lgkmcnt(2)
	s_nop 0
	v_mfma_f32_32x32x16_bf16 v[64:79], v[128:131], v[132:135], v[64:79]
	s_waitcnt lgkmcnt(0)
	v_mfma_f32_32x32x16_bf16 v[48:63], v[136:139], v[132:135], v[48:63]
	ds_read_b64_tr_b16 v[128:129], v225 offset:17536
	ds_read_b64_tr_b16 v[130:131], v225 offset:20096
	ds_read_b64_tr_b16 v[138:139], v225 offset:20160
	ds_read_b64_tr_b16 v[136:137], v225 offset:17600
	s_waitcnt lgkmcnt(2)
	v_mfma_f32_32x32x16_bf16 v[32:47], v[128:131], v[132:135], v[32:47]
	s_waitcnt lgkmcnt(0)
	v_mfma_f32_32x32x16_bf16 v[0:15], v[136:139], v[132:135], v[0:15]
	ds_read_b64_tr_b16 v[128:129], v225 offset:22528
	ds_read_b64_tr_b16 v[130:131], v225 offset:25088
	ds_read_b64_tr_b16 v[138:139], v225 offset:25152
	ds_read_b64_tr_b16 v[136:137], v225 offset:22592
	v_cvt_pk_bf16_f32 v132, v152, v153
	v_cvt_pk_bf16_f32 v133, v154, v155
	v_cvt_pk_bf16_f32 v134, v140, v141
	v_cvt_pk_bf16_f32 v135, v142, v143
	s_waitcnt lgkmcnt(2)
	s_nop 0
	v_mfma_f32_32x32x16_bf16 v[64:79], v[128:131], v[132:135], v[64:79]
	s_waitcnt lgkmcnt(0)
	v_mfma_f32_32x32x16_bf16 v[48:63], v[136:139], v[132:135], v[48:63]
	ds_read_b64_tr_b16 v[128:129], v225 offset:22656
	ds_read_b64_tr_b16 v[130:131], v225 offset:25216
	ds_read_b64_tr_b16 v[138:139], v225 offset:25280
	ds_read_b64_tr_b16 v[136:137], v225 offset:22720
	s_waitcnt lgkmcnt(2)
	v_mfma_f32_32x32x16_bf16 v[32:47], v[128:131], v[132:135], v[32:47]
	s_waitcnt lgkmcnt(0)
	v_mfma_f32_32x32x16_bf16 v[0:15], v[136:139], v[132:135], v[0:15]
	ds_read_b64_tr_b16 v[128:129], v225 offset:27648
	ds_read_b64_tr_b16 v[130:131], v225 offset:30208
	ds_read_b64_tr_b16 v[138:139], v225 offset:30272
	ds_read_b64_tr_b16 v[136:137], v225 offset:27712
	v_cvt_pk_bf16_f32 v132, v144, v145
	v_cvt_pk_bf16_f32 v133, v234, v235
	v_cvt_pk_bf16_f32 v134, v148, v149
	v_cvt_pk_bf16_f32 v135, v238, v239
	s_waitcnt lgkmcnt(2)
	s_nop 0
	v_mfma_f32_32x32x16_bf16 v[64:79], v[128:131], v[132:135], v[64:79]
	s_waitcnt lgkmcnt(0)
	v_mfma_f32_32x32x16_bf16 v[48:63], v[136:139], v[132:135], v[48:63]
	ds_read_b64_tr_b16 v[128:129], v225 offset:27776
	ds_read_b64_tr_b16 v[130:131], v225 offset:30336
	ds_read_b64_tr_b16 v[138:139], v225 offset:30400
	ds_read_b64_tr_b16 v[136:137], v225 offset:27840
	s_waitcnt lgkmcnt(2)
	v_mfma_f32_32x32x16_bf16 v[32:47], v[128:131], v[132:135], v[32:47]
	s_waitcnt lgkmcnt(0)
	v_mfma_f32_32x32x16_bf16 v[0:15], v[136:139], v[132:135], v[0:15]
	ds_read_b64_tr_b16 v[128:129], v225 offset:32768
	ds_read_b64_tr_b16 v[130:131], v225 offset:35328
	ds_read_b64_tr_b16 v[138:139], v225 offset:35392
	ds_read_b64_tr_b16 v[136:137], v225 offset:32832
	v_cvt_pk_bf16_f32 v132, v240, v241
	v_cvt_pk_bf16_f32 v133, v242, v243
	v_cvt_pk_bf16_f32 v134, v156, v157
	v_cvt_pk_bf16_f32 v135, v158, v159
	s_waitcnt lgkmcnt(2)
	s_nop 0
	v_mfma_f32_32x32x16_bf16 v[64:79], v[128:131], v[132:135], v[64:79]
	s_waitcnt lgkmcnt(0)
	v_mfma_f32_32x32x16_bf16 v[48:63], v[136:139], v[132:135], v[48:63]
	ds_read_b64_tr_b16 v[128:129], v225 offset:32896
	ds_read_b64_tr_b16 v[130:131], v225 offset:35456
	ds_read_b64_tr_b16 v[138:139], v225 offset:35520
	ds_read_b64_tr_b16 v[136:137], v225 offset:32960
	s_waitcnt lgkmcnt(2)
	v_mfma_f32_32x32x16_bf16 v[32:47], v[128:131], v[132:135], v[32:47]
	s_waitcnt lgkmcnt(0)
	v_mfma_f32_32x32x16_bf16 v[0:15], v[136:139], v[132:135], v[0:15]
	ds_read_b128 v[144:147], v222 offset:128
	ds_read_b128 v[232:235], v230 offset:160
	ds_read_b128 v[236:239], v222 offset:160
	ds_read_b128 v[148:151], v230 offset:8832
	ds_read_b128 v[240:243], v230 offset:8864
	v_mov_b32_e32 v228, v200
	v_mov_b32_e32 v226, v231

; template <int NS, int SI>
; __device__ __forceinline__ void attn_stream(const unsigned char* kbase, const unsigned char* vbase, const unsigned char* q_rd, bool mask_tail, int last_valid, int hh, float sc,
;                                             f32x16 (&O)[4], float& mrun, float& lrun) {
;     ...
;     const float mn = fmaxf(mrun, mx * sc);
;     const float alpha = __builtin_amdgcn_exp2f(mrun - mn);
;     mrun = mn;
;     f32x2 ls2 = {0.f, 0.f};
;     const f32x2 sc2 = {sc, sc}, mn2 = {mn, mn};
; #pragma unroll
;     for (int r = 0; r < 16; r += 2) {
;         const f32x2 t0 = (f32x2){S0[r], S0[r + 1]} * sc2 - mn2, t1 = (f32x2){S1[r], S1[r + 1]} * sc2 - mn2;
;         const f32x2 p0 = {__builtin_amdgcn_exp2f(t0.x), __builtin_amdgcn_exp2f(t0.y)}, p1 = {__builtin_amdgcn_exp2f(t1.x), __builtin_amdgcn_exp2f(t1.y)};
;         S0[r] = p0.x; S0[r + 1] = p0.y; S1[r] = p1.x; S1[r + 1] = p1.y; ls2 += p0 + p1;
;     }
;     lrun = lrun * alpha + (ls2.x + ls2.y);
;     if (__any(alpha != 1.0f)) {
; #pragma unroll
;         for (int d = 0; d < 4; ++d) O[d] = O[d] * alpha;
.LBB0_1179:
	v_pk_fma_f32 v[128:129], v[128:129], s[58:59], v[200:201] op_sel_hi:[1,0,0] neg_lo:[0,0,1] neg_hi:[0,0,1]
	v_pk_fma_f32 v[144:145], v[144:145], s[58:59], v[200:201] op_sel_hi:[1,0,0] neg_lo:[0,0,1] neg_hi:[0,0,1]
	v_exp_f32_e32 v232, v128
	v_exp_f32_e32 v233, v129
	v_exp_f32_e32 v144, v144
	v_exp_f32_e32 v145, v145
	v_pk_fma_f32 v[128:129], v[130:131], s[58:59], v[200:201] op_sel_hi:[1,0,0] neg_lo:[0,0,1] neg_hi:[0,0,1]
	v_pk_fma_f32 v[130:131], v[146:147], s[58:59], v[200:201] op_sel_hi:[1,0,0] neg_lo:[0,0,1] neg_hi:[0,0,1]
	v_exp_f32_e32 v146, v128
	v_exp_f32_e32 v147, v129
	v_exp_f32_e32 v234, v130
	v_exp_f32_e32 v235, v131
	v_pk_fma_f32 v[132:133], v[132:133], s[58:59], v[200:201] op_sel_hi:[1,0,0] neg_lo:[0,0,1] neg_hi:[0,0,1]
	v_pk_fma_f32 v[148:149], v[148:149], s[58:59], v[200:201] op_sel_hi:[1,0,0] neg_lo:[0,0,1] neg_hi:[0,0,1]
	v_exp_f32_e32 v236, v132
	v_exp_f32_e32 v237, v133
	v_exp_f32_e32 v148, v148
	v_exp_f32_e32 v149, v149
	v_pk_fma_f32 v[132:133], v[134:135], s[58:59], v[200:201] op_sel_hi:[1,0,0] neg_lo:[0,0,1] neg_hi:[0,0,1]
	v_pk_fma_f32 v[134:135], v[150:151], s[58:59], v[200:201] op_sel_hi:[1,0,0] neg_lo:[0,0,1] neg_hi:[0,0,1]
	v_exp_f32_e32 v150, v132
	v_exp_f32_e32 v151, v133
	v_exp_f32_e32 v238, v134
	v_exp_f32_e32 v239, v135
	v_pk_fma_f32 v[132:133], v[136:137], s[58:59], v[200:201] op_sel_hi:[1,0,0] neg_lo:[0,0,1] neg_hi:[0,0,1]
	v_pk_fma_f32 v[134:135], v[152:153], s[58:59], v[200:201] op_sel_hi:[1,0,0] neg_lo:[0,0,1] neg_hi:[0,0,1]
	v_pk_add_f32 v[128:129], v[144:145], v[232:233]
	v_exp_f32_e32 v152, v132
	v_exp_f32_e32 v153, v133
	v_exp_f32_e32 v240, v134
	v_exp_f32_e32 v241, v135
	v_pk_fma_f32 v[132:133], v[138:139], s[58:59], v[200:201] op_sel_hi:[1,0,0] neg_lo:[0,0,1] neg_hi:[0,0,1]
	v_pk_fma_f32 v[134:135], v[154:155], s[58:59], v[200:201] op_sel_hi:[1,0,0] neg_lo:[0,0,1] neg_hi:[0,0,1]
	v_pk_add_f32 v[130:131], v[234:235], v[146:147]
	v_exp_f32_e32 v154, v132
	v_exp_f32_e32 v155, v133
	v_exp_f32_e32 v242, v134
	v_exp_f32_e32 v243, v135
	v_pk_fma_f32 v[132:133], v[140:141], s[58:59], v[200:201] op_sel_hi:[1,0,0] neg_lo:[0,0,1] neg_hi:[0,0,1]
	v_pk_fma_f32 v[134:135], v[156:157], s[58:59], v[200:201] op_sel_hi:[1,0,0] neg_lo:[0,0,1] neg_hi:[0,0,1]
	v_pk_add_f32 v[128:129], v[130:131], v[128:129]
	v_pk_add_f32 v[130:131], v[148:149], v[236:237]
	v_exp_f32_e32 v140, v132
	v_exp_f32_e32 v141, v133
	v_exp_f32_e32 v156, v134
	v_exp_f32_e32 v157, v135
	v_pk_fma_f32 v[132:133], v[142:143], s[58:59], v[200:201] op_sel_hi:[1,0,0] neg_lo:[0,0,1] neg_hi:[0,0,1]
	v_pk_fma_f32 v[134:135], v[158:159], s[58:59], v[200:201] op_sel_hi:[1,0,0] neg_lo:[0,0,1] neg_hi:[0,0,1]
	v_pk_add_f32 v[128:129], v[130:131], v[128:129]
	v_pk_add_f32 v[130:131], v[238:239], v[150:151]
	v_exp_f32_e32 v142, v132
	v_exp_f32_e32 v143, v133
	v_exp_f32_e32 v158, v134
	v_exp_f32_e32 v159, v135
	v_pk_add_f32 v[128:129], v[130:131], v[128:129]
	v_pk_add_f32 v[130:131], v[240:241], v[152:153]
	v_pk_add_f32 v[132:133], v[242:243], v[154:155]
	v_pk_add_f32 v[134:135], v[156:157], v[140:141]
	v_pk_add_f32 v[136:137], v[158:159], v[142:143]
	v_pk_add_f32 v[128:129], v[130:131], v[128:129]
	v_pk_add_f32 v[132:133], v[134:135], v[132:133]
	v_pk_add_f32 v[128:129], v[136:137], v[128:129]
	v_pk_add_f32 v[128:129], v[132:133], v[128:129]
	v_add_f32_e32 v230, v128, v129
	s_cbranch_vccz .Lsm1_norescale
	v_sub_f32_e32 v202, v229, v200
	v_exp_f32_e32 v202, v202
	s_nop 0
	v_pk_mul_f32 v[126:127], v[126:127], v[202:203] op_sel_hi:[1,0]
	v_pk_mul_f32 v[124:125], v[124:125], v[202:203] op_sel_hi:[1,0]
	v_pk_mul_f32 v[122:123], v[122:123], v[202:203] op_sel_hi:[1,0]
	v_pk_mul_f32 v[120:121], v[120:121], v[202:203] op_sel_hi:[1,0]
	v_pk_mul_f32 v[118:119], v[118:119], v[202:203] op_sel_hi:[1,0]
	v_pk_mul_f32 v[116:117], v[116:117], v[202:203] op_sel_hi:[1,0]
	v_pk_mul_f32 v[114:115], v[114:115], v[202:203] op_sel_hi:[1,0]
	v_pk_mul_f32 v[112:113], v[112:113], v[202:203] op_sel_hi:[1,0]
	v_pk_mul_f32 v[110:111], v[110:111], v[202:203] op_sel_hi:[1,0]
	v_pk_mul_f32 v[108:109], v[108:109], v[202:203] op_sel_hi:[1,0]
	v_pk_mul_f32 v[106:107], v[106:107], v[202:203] op_sel_hi:[1,0]
	v_pk_mul_f32 v[104:105], v[104:105], v[202:203] op_sel_hi:[1,0]
	v_pk_mul_f32 v[102:103], v[102:103], v[202:203] op_sel_hi:[1,0]
	v_pk_mul_f32 v[100:101], v[100:101], v[202:203] op_sel_hi:[1,0]
	v_pk_mul_f32 v[98:99], v[98:99], v[202:203] op_sel_hi:[1,0]
	v_pk_mul_f32 v[96:97], v[96:97], v[202:203] op_sel_hi:[1,0]
	v_pk_mul_f32 v[94:95], v[94:95], v[202:203] op_sel_hi:[1,0]
	v_pk_mul_f32 v[92:93], v[92:93], v[202:203] op_sel_hi:[1,0]
	v_pk_mul_f32 v[90:91], v[90:91], v[202:203] op_sel_hi:[1,0]
	v_pk_mul_f32 v[88:89], v[88:89], v[202:203] op_sel_hi:[1,0]
	v_pk_mul_f32 v[86:87], v[86:87], v[202:203] op_sel_hi:[1,0]
	v_pk_mul_f32 v[84:85], v[84:85], v[202:203] op_sel_hi:[1,0]
	v_pk_mul_f32 v[82:83], v[82:83], v[202:203] op_sel_hi:[1,0]
	v_pk_mul_f32 v[80:81], v[80:81], v[202:203] op_sel_hi:[1,0]
	v_pk_mul_f32 v[30:31], v[30:31], v[202:203] op_sel_hi:[1,0]
	v_pk_mul_f32 v[28:29], v[28:29], v[202:203] op_sel_hi:[1,0]
	v_pk_mul_f32 v[26:27], v[26:27], v[202:203] op_sel_hi:[1,0]
	v_pk_mul_f32 v[24:25], v[24:25], v[202:203] op_sel_hi:[1,0]
	v_pk_mul_f32 v[22:23], v[22:23], v[202:203] op_sel_hi:[1,0]
	v_pk_mul_f32 v[20:21], v[20:21], v[202:203] op_sel_hi:[1,0]
	v_pk_mul_f32 v[18:19], v[18:19], v[202:203] op_sel_hi:[1,0]
	v_pk_mul_f32 v[16:17], v[16:17], v[202:203] op_sel_hi:[1,0]
; template <int NS, int SI>
; __device__ __forceinline__ void attn_stream(const unsigned char* kbase, const unsigned char* vbase, const unsigned char* q_rd, bool mask_tail, int last_valid, int hh, float sc,
;                                             f32x16 (&O)[4], float& mrun, float& lrun) {
;     ...
;     lrun = lrun * alpha + (ls2.x + ls2.y);
;     if (__any(alpha != 1.0f)) {
; #pragma unroll
;         for (int d = 0; d < 4; ++d) O[d] = O[d] * alpha;
;     }
;     ...
;     __builtin_amdgcn_sched_barrier(0);
;     PV_GROUP(S0, 0, 0) PV_GROUP(S0, 0, 1) PV_GROUP(S1, 1, 0) PV_GROUP(S1, 1, 1)
.Lsm1_norescale:
	v_fmac_f32_e32 v230, v227, v202
	ds_read_b64_tr_b16 v[128:129], v225 offset:17408
	ds_read_b64_tr_b16 v[130:131], v225 offset:19968
	ds_read_b64_tr_b16 v[138:139], v225 offset:20032
	ds_read_b64_tr_b16 v[136:137], v225 offset:17472
	v_cvt_pk_bf16_f32 v132, v232, v233
	v_cvt_pk_bf16_f32 v133, v146, v147
	v_cvt_pk_bf16_f32 v134, v236, v237
	v_cvt_pk_bf16_f32 v135, v150, v151
	s_waitcnt lgkmcnt(2)
	s_nop 0
	v_mfma_f32_32x32x16_bf16 v[112:127], v[128:131], v[132:135], v[112:127]
	s_waitcnt lgkmcnt(0)
	v_mfma_f32_32x32x16_bf16 v[96:111], v[136:139], v[132:135], v[96:111]
	ds_read_b64_tr_b16 v[128:129], v225 offset:17536
	ds_read_b64_tr_b16 v[130:131], v225 offset:20096
	ds_read_b64_tr_b16 v[138:139], v225 offset:20160
	ds_read_b64_tr_b16 v[136:137], v225 offset:17600
	s_waitcnt lgkmcnt(2)
	v_mfma_f32_32x32x16_bf16 v[80:95], v[128:131], v[132:135], v[80:95]
	s_waitcnt lgkmcnt(0)
	v_mfma_f32_32x32x16_bf16 v[16:31], v[136:139], v[132:135], v[16:31]
	ds_read_b64_tr_b16 v[128:129], v225 offset:22528
	ds_read_b64_tr_b16 v[130:131], v225 offset:25088
	ds_read_b64_tr_b16 v[138:139], v225 offset:25152
	ds_read_b64_tr_b16 v[136:137], v225 offset:22592
	v_cvt_pk_bf16_f32 v132, v152, v153
	v_cvt_pk_bf16_f32 v133, v154, v155
	v_cvt_pk_bf16_f32 v134, v140, v141
	v_cvt_pk_bf16_f32 v135, v142, v143
	s_waitcnt lgkmcnt(2)
	s_nop 0
	v_mfma_f32_32x32x16_bf16 v[112:127], v[128:131], v[132:135], v[112:127]
	s_waitcnt lgkmcnt(0)
	v_mfma_f32_32x32x16_bf16 v[96:111], v[136:139], v[132:135], v[96:111]
	ds_read_b64_tr_b16 v[128:129], v225 offset:22656
	ds_read_b64_tr_b16 v[130:131], v225 offset:25216
	ds_read_b64_tr_b16 v[138:139], v225 offset:25280
	ds_read_b64_tr_b16 v[136:137], v225 offset:22720
	s_waitcnt lgkmcnt(2)
	v_mfma_f32_32x32x16_bf16 v[80:95], v[128:131], v[132:135], v[80:95]
	s_waitcnt lgkmcnt(0)
	v_mfma_f32_32x32x16_bf16 v[16:31], v[136:139], v[132:135], v[16:31]
	ds_read_b64_tr_b16 v[128:129], v225 offset:27648
	ds_read_b64_tr_b16 v[130:131], v225 offset:30208
	ds_read_b64_tr_b16 v[138:139], v225 offset:30272
	ds_read_b64_tr_b16 v[136:137], v225 offset:27712
	v_cvt_pk_bf16_f32 v132, v144, v145
	v_cvt_pk_bf16_f32 v133, v234, v235
	v_cvt_pk_bf16_f32 v134, v148, v149
	v_cvt_pk_bf16_f32 v135, v238, v239
	s_waitcnt lgkmcnt(2)
	s_nop 0
	v_mfma_f32_32x32x16_bf16 v[112:127], v[128:131], v[132:135], v[112:127]
	s_waitcnt lgkmcnt(0)
	v_mfma_f32_32x32x16_bf16 v[96:111], v[136:139], v[132:135], v[96:111]
	ds_read_b64_tr_b16 v[128:129], v225 offset:27776
	ds_read_b64_tr_b16 v[130:131], v225 offset:30336
	ds_read_b64_tr_b16 v[138:139], v225 offset:30400
	ds_read_b64_tr_b16 v[136:137], v225 offset:27840
	s_waitcnt lgkmcnt(2)
	v_mfma_f32_32x32x16_bf16 v[80:95], v[128:131], v[132:135], v[80:95]
	s_waitcnt lgkmcnt(0)
	v_mfma_f32_32x32x16_bf16 v[16:31], v[136:139], v[132:135], v[16:31]
	ds_read_b64_tr_b16 v[128:129], v225 offset:32768
	ds_read_b64_tr_b16 v[130:131], v225 offset:35328
	ds_read_b64_tr_b16 v[138:139], v225 offset:35392
	ds_read_b64_tr_b16 v[136:137], v225 offset:32832
	v_cvt_pk_bf16_f32 v132, v240, v241
	v_cvt_pk_bf16_f32 v133, v242, v243
	v_cvt_pk_bf16_f32 v134, v156, v157
	v_cvt_pk_bf16_f32 v135, v158, v159
	s_waitcnt lgkmcnt(2)
	s_nop 0
	v_mfma_f32_32x32x16_bf16 v[112:127], v[128:131], v[132:135], v[112:127]
	s_waitcnt lgkmcnt(0)
	v_mfma_f32_32x32x16_bf16 v[96:111], v[136:139], v[132:135], v[96:111]
	ds_read_b64_tr_b16 v[128:129], v225 offset:32896
	ds_read_b64_tr_b16 v[130:131], v225 offset:35456
	ds_read_b64_tr_b16 v[138:139], v225 offset:35520
	ds_read_b64_tr_b16 v[136:137], v225 offset:32960
	s_waitcnt lgkmcnt(2)
	v_mfma_f32_32x32x16_bf16 v[80:95], v[128:131], v[132:135], v[80:95]
	s_waitcnt lgkmcnt(0)
	v_mfma_f32_32x32x16_bf16 v[16:31], v[136:139], v[132:135], v[16:31]
	v_mov_b32_e32 v229, v200
	v_mov_b32_e32 v227, v230
	s_or_b64 exec, exec, s[64:65]
	s_and_b64 vcc, exec, s[44:45]
	s_cbranch_vccz .LBB0_1171
	s_branch .LBB0_1172
